# p6/p7 GEMM K-loops restructured like the in-proj loop (DMA pieces between MFMA groups, kk=1 fragments prefetched during kk=0 MFMAs)
# baseline (speedup 1.0000x reference)
; template <int GATE>
; DEVI void gemm_core_t(f32x4 (&acc)[4][4], const bfu* __restrict__ A, int lda,
;                     const bfu* __restrict__ B, int ldb, int K, char* smem, int tid, const bfu* __restrict__ B2 = nullptr) {
;     ...
;   for (int t = 0; t < nt; ++t) {
;     asm volatile("s_waitcnt vmcnt(0)" ::: "memory");
;     __syncthreads();
;     char* cur = smem + (t & 1) * 32768;
;     if (t + 1 < nt) {
;       char* nx = smem + ((t + 1) & 1) * 32768;
;       stage_tile(A, lda, (t + 1) * 64, nx, tid);
;       if (GATE) stage_tile_gate(B, B2, (t + 1) * 64, nx + 16384, tid); else stage_tile(B, ldb, (t + 1) * 64, nx + 16384, tid);
;     }
; #pragma unroll
;     for (int kk = 0; kk < 2; ++kk) {
;       bf16x8 af[4], bfr[4];
; #pragma unroll
;       for (int m = 0; m < 4; ++m) af[m] = ldfrag(cur, wr * 64 + m * 16 + fr, kk * 4 + fq);
; #pragma unroll
;       for (int n = 0; n < 4; ++n) bfr[n] = ldfrag(cur + 16384, wc * 64 + n * 16 + fr, kk * 4 + fq);
; #pragma unroll
;       for (int m = 0; m < 4; ++m)
; #pragma unroll
;         for (int n = 0; n < 4; ++n)
;           acc[m][n] = __builtin_amdgcn_mfma_f32_16x16x32_bf16(af[m], bfr[n], acc[m][n], 0, 0, 0);
;     }
.LBB0_735:
	s_add_i32 s27, s24, 0xffff8000
	s_and_b32 s41, s27, 0x8000
	s_and_b32 s27, s24, 0x8000
	v_add_u32_e32 v125, s27, v101
	v_or_b32_e32 v127, s41, v146
	v_readfirstlane_b32 s49, v125
	v_add_u32_e32 v125, v127, v148
	v_add_u32_e32 v127, v127, v147
	s_waitcnt vmcnt(0)
	s_waitcnt vmcnt(0) lgkmcnt(0)
	s_barrier
	ds_read_b128 v[158:161], v127
	ds_read_b128 v[174:177], v125 offset:16384
	ds_read_b128 v[178:181], v125 offset:18432
	ds_read_b128 v[196:199], v125 offset:20480
	ds_read_b128 v[200:203], v125 offset:22528
	ds_read_b128 v[162:165], v127 offset:2048
	ds_read_b128 v[166:169], v127 offset:4096
	ds_read_b128 v[170:173], v127 offset:6144
	v_lshl_add_u64 v[224:225], v[130:131], 0, s[52:53]
	s_mov_b32 m0, s49
	s_add_i32 s49, s49, 0x1000
	global_load_lds_dwordx4 v[224:225], off
	v_or_b32_e32 v125, s41, v149
	v_add_u32_e32 v127, v125, v147
	v_add_u32_e32 v125, v125, v148
	ds_read_b128 v[208:211], v125 offset:16384
	ds_read_b128 v[212:215], v125 offset:18432
	ds_read_b128 v[216:219], v125 offset:20480
	ds_read_b128 v[220:223], v125 offset:22528
	v_lshl_add_u64 v[224:225], v[132:133], 0, s[52:53]
	s_mov_b32 m0, s49
	s_add_i32 s49, s49, 0x1000
	global_load_lds_dwordx4 v[224:225], off
	s_waitcnt lgkmcnt(7)
	v_mfma_f32_16x16x32_bf16 v[60:63], v[158:161], v[174:177], v[60:63]
	v_mfma_f32_16x16x32_bf16 v[56:59], v[158:161], v[178:181], v[56:59]
	v_mfma_f32_16x16x32_bf16 v[52:55], v[158:161], v[196:199], v[52:55]
	v_mfma_f32_16x16x32_bf16 v[48:51], v[158:161], v[200:203], v[48:51]
	ds_read_b128 v[158:161], v127
	v_lshl_add_u64 v[224:225], v[134:135], 0, s[52:53]
	s_mov_b32 m0, s49
	s_add_i32 s49, s49, 0x1000
	global_load_lds_dwordx4 v[224:225], off
	s_waitcnt lgkmcnt(7)
	v_mfma_f32_16x16x32_bf16 v[44:47], v[162:165], v[174:177], v[44:47]
	v_mfma_f32_16x16x32_bf16 v[40:43], v[162:165], v[178:181], v[40:43]
	v_mfma_f32_16x16x32_bf16 v[36:39], v[162:165], v[196:199], v[36:39]
	v_mfma_f32_16x16x32_bf16 v[32:35], v[162:165], v[200:203], v[32:35]
	ds_read_b128 v[162:165], v127 offset:2048
	v_lshl_add_u64 v[224:225], v[136:137], 0, s[52:53]
	s_mov_b32 m0, s49
	s_add_i32 s49, s49, 0x1000
	global_load_lds_dwordx4 v[224:225], off
	s_waitcnt lgkmcnt(7)
	v_mfma_f32_16x16x32_bf16 v[28:31], v[166:169], v[174:177], v[28:31]
	v_mfma_f32_16x16x32_bf16 v[24:27], v[166:169], v[178:181], v[24:27]
	v_mfma_f32_16x16x32_bf16 v[20:23], v[166:169], v[196:199], v[20:23]
	v_mfma_f32_16x16x32_bf16 v[16:19], v[166:169], v[200:203], v[16:19]
	ds_read_b128 v[166:169], v127 offset:4096
	v_lshl_add_u64 v[224:225], v[138:139], 0, s[52:53]
	s_mov_b32 m0, s49
	s_add_i32 s49, s49, 0x1000
	global_load_lds_dwordx4 v[224:225], off
	s_waitcnt lgkmcnt(7)
	v_mfma_f32_16x16x32_bf16 v[12:15], v[170:173], v[174:177], v[12:15]
	v_mfma_f32_16x16x32_bf16 v[8:11], v[170:173], v[178:181], v[8:11]
	v_mfma_f32_16x16x32_bf16 v[4:7], v[170:173], v[196:199], v[4:7]
	v_mfma_f32_16x16x32_bf16 v[0:3], v[170:173], v[200:203], v[0:3]
	ds_read_b128 v[170:173], v127 offset:6144
	v_lshl_add_u64 v[224:225], v[140:141], 0, s[52:53]
	s_mov_b32 m0, s49
	s_add_i32 s49, s49, 0x1000
	global_load_lds_dwordx4 v[224:225], off
	s_waitcnt lgkmcnt(3)
	v_mfma_f32_16x16x32_bf16 v[60:63], v[158:161], v[208:211], v[60:63]
	v_mfma_f32_16x16x32_bf16 v[56:59], v[158:161], v[212:215], v[56:59]
	v_mfma_f32_16x16x32_bf16 v[52:55], v[158:161], v[216:219], v[52:55]
	v_mfma_f32_16x16x32_bf16 v[48:51], v[158:161], v[220:223], v[48:51]
	v_lshl_add_u64 v[224:225], v[142:143], 0, s[52:53]
	s_mov_b32 m0, s49
	s_add_i32 s49, s49, 0x1000
	global_load_lds_dwordx4 v[224:225], off
	s_waitcnt lgkmcnt(2)
	v_mfma_f32_16x16x32_bf16 v[44:47], v[162:165], v[208:211], v[44:47]
	v_mfma_f32_16x16x32_bf16 v[40:43], v[162:165], v[212:215], v[40:43]
	v_mfma_f32_16x16x32_bf16 v[36:39], v[162:165], v[216:219], v[36:39]
	v_mfma_f32_16x16x32_bf16 v[32:35], v[162:165], v[220:223], v[32:35]
	v_lshl_add_u64 v[224:225], v[144:145], 0, s[52:53]
	s_mov_b32 m0, s49
	s_add_i32 s49, s49, 0x1000
	global_load_lds_dwordx4 v[224:225], off
	s_waitcnt lgkmcnt(1)
	v_mfma_f32_16x16x32_bf16 v[28:31], v[166:169], v[208:211], v[28:31]
	v_mfma_f32_16x16x32_bf16 v[24:27], v[166:169], v[212:215], v[24:27]
	v_mfma_f32_16x16x32_bf16 v[20:23], v[166:169], v[216:219], v[20:23]
	v_mfma_f32_16x16x32_bf16 v[16:19], v[166:169], v[220:223], v[16:19]
	s_waitcnt lgkmcnt(0)
	v_mfma_f32_16x16x32_bf16 v[12:15], v[170:173], v[208:211], v[12:15]
	v_mfma_f32_16x16x32_bf16 v[8:11], v[170:173], v[212:215], v[8:11]
	v_mfma_f32_16x16x32_bf16 v[4:7], v[170:173], v[216:219], v[4:7]
	v_mfma_f32_16x16x32_bf16 v[0:3], v[170:173], v[220:223], v[0:3]
	s_add_u32 s52, s52, 0x80
	s_addc_u32 s53, s53, 0
	s_add_i32 s24, s24, 0x8000
	s_cmpk_lg_i32 s52, 0x780
	s_cbranch_scc1 .LBB0_735
	v_add_u32_e32 v125, s27, v146
	v_add_u32_e32 v127, v125, v147
	s_waitcnt vmcnt(0)
	s_waitcnt vmcnt(0)
	s_barrier
; template <int GATE>
; DEVI void gemm_core_t(f32x4 (&acc)[4][4], const bfu* __restrict__ A, int lda,
;                     const bfu* __restrict__ B, int ldb, int K, char* smem, int tid, const bfu* __restrict__ B2 = nullptr) {
;     ...
; #pragma unroll
;     for (int kk = 0; kk < 2; ++kk) {
;       bf16x8 af[4], bfr[4];
; #pragma unroll
;       for (int m = 0; m < 4; ++m) af[m] = ldfrag(cur, wr * 64 + m * 16 + fr, kk * 4 + fq);
; #pragma unroll
;       for (int n = 0; n < 4; ++n) bfr[n] = ldfrag(cur + 16384, wc * 64 + n * 16 + fr, kk * 4 + fq);
; #pragma unroll
;       for (int m = 0; m < 4; ++m)
; #pragma unroll
;         for (int n = 0; n < 4; ++n)
;           acc[m][n] = __builtin_amdgcn_mfma_f32_16x16x32_bf16(af[m], bfr[n], acc[m][n], 0, 0, 0);
;     }
; DEVI void epi_stage_f32(const f32x4 (&acc)[4][4], char* smem, int tid) {
;   const int wid = tid >> 6, lane = tid & 63, wr = wid >> 1, wc = wid & 1, fr = lane & 15, fq = lane >> 4;
;   float* T = reinterpret_cast<float*>(smem);
;   __syncthreads();
; #pragma unroll
;   for (int m = 0; m < 4; ++m)
; #pragma unroll
;     for (int n = 0; n < 4; ++n)
; #pragma unroll
;       for (int j = 0; j < 4; ++j)
;         T[(wr * 64 + m * 16 + fq * 4 + j) * 128 + wc * 64 + n * 16 + fr] = acc[m][n][j];
;   __syncthreads();
	ds_read_b128 v[130:133], v127
	v_add_u32_e32 v125, v125, v148
	ds_read_b128 v[134:137], v125 offset:16384
	ds_read_b128 v[138:141], v127 offset:2048
	ds_read_b128 v[142:145], v125 offset:18432
	ds_read_b128 v[158:161], v125 offset:20480
	ds_read_b128 v[162:165], v125 offset:22528
	s_waitcnt lgkmcnt(3)
	v_mfma_f32_16x16x32_bf16 v[44:47], v[138:141], v[134:137], v[44:47]
	v_add_u32_e32 v125, s27, v149
	s_add_u32 s42, s30, s42
	s_addc_u32 s43, s31, s43
	v_mfma_f32_16x16x32_bf16 v[60:63], v[130:133], v[134:137], v[60:63]
	s_add_u32 s44, s30, s44
	s_addc_u32 s45, s31, s45
	v_add_u32_e32 v157, 0x6400, v150
	s_waitcnt lgkmcnt(2)
	v_mfma_f32_16x16x32_bf16 v[56:59], v[130:133], v[142:145], v[56:59]
	s_add_u32 s50, s30, s50
	s_addc_u32 s51, s31, s51
	s_lshl_b64 s[46:47], s[46:47], 7
	s_waitcnt lgkmcnt(1)
	v_mfma_f32_16x16x32_bf16 v[52:55], v[130:133], v[158:161], v[52:55]
	s_mov_b32 s24, 0
	s_waitcnt lgkmcnt(0)
	v_mfma_f32_16x16x32_bf16 v[48:51], v[130:133], v[162:165], v[48:51]
	v_mfma_f32_16x16x32_bf16 v[40:43], v[138:141], v[142:145], v[40:43]
	v_mfma_f32_16x16x32_bf16 v[36:39], v[138:141], v[158:161], v[36:39]
	v_mfma_f32_16x16x32_bf16 v[32:35], v[138:141], v[162:165], v[32:35]
	ds_read_b128 v[130:133], v127 offset:4096
	ds_read_b128 v[138:141], v127 offset:6144
	v_add_u32_e32 v127, v125, v147
	v_add_u32_e32 v125, v125, v148
	s_waitcnt lgkmcnt(1)
	v_mfma_f32_16x16x32_bf16 v[28:31], v[130:133], v[134:137], v[28:31]
	v_mfma_f32_16x16x32_bf16 v[24:27], v[130:133], v[142:145], v[24:27]
	v_mfma_f32_16x16x32_bf16 v[20:23], v[130:133], v[158:161], v[20:23]
	v_mfma_f32_16x16x32_bf16 v[16:19], v[130:133], v[162:165], v[16:19]
	ds_read_b128 v[130:133], v127
	s_waitcnt lgkmcnt(1)
	v_mfma_f32_16x16x32_bf16 v[12:15], v[138:141], v[134:137], v[12:15]
	ds_read_b128 v[134:137], v125 offset:16384
	v_mfma_f32_16x16x32_bf16 v[8:11], v[138:141], v[142:145], v[8:11]
	v_mfma_f32_16x16x32_bf16 v[4:7], v[138:141], v[158:161], v[4:7]
	ds_read_b128 v[142:145], v127 offset:2048
	ds_read_b128 v[158:161], v125 offset:18432
	ds_read_b128 v[166:169], v125 offset:22528
	v_mfma_f32_16x16x32_bf16 v[0:3], v[138:141], v[162:165], v[0:3]
	ds_read_b128 v[162:165], v125 offset:20480
	ds_read_b128 v[170:173], v127 offset:4096
	ds_read_b128 v[174:177], v127 offset:6144
	v_add_u32_e32 v140, 0x400, v150
	s_waitcnt lgkmcnt(6)
	v_mfma_f32_16x16x32_bf16 v[60:63], v[130:133], v[134:137], v[60:63]
	v_add_u32_e32 v141, 0x2000, v150
	s_waitcnt lgkmcnt(0)
	s_barrier
	v_mfma_f32_16x16x32_bf16 v[56:59], v[130:133], v[158:161], v[56:59]
	s_nop 7
	ds_write2_b32 v150, v60, v56 offset1:16
	ds_write2_b32 v150, v61, v57 offset0:128 offset1:144
	v_mfma_f32_16x16x32_bf16 v[52:55], v[130:133], v[162:165], v[52:55]
	ds_write2_b32 v140, v62, v58 offset1:16
	ds_write2_b32 v140, v63, v59 offset0:128 offset1:144
	v_mfma_f32_16x16x32_bf16 v[48:51], v[130:133], v[166:169], v[48:51]
	s_nop 7
	ds_write2_b32 v150, v52, v48 offset0:32 offset1:48
	ds_write2_b32 v150, v53, v49 offset0:160 offset1:176
	ds_write2_b32 v140, v54, v50 offset0:32 offset1:48
	v_mfma_f32_16x16x32_bf16 v[44:47], v[142:145], v[134:137], v[44:47]
	ds_write2_b32 v140, v55, v51 offset0:160 offset1:176
	v_mfma_f32_16x16x32_bf16 v[40:43], v[142:145], v[158:161], v[40:43]
	v_mfma_f32_16x16x32_bf16 v[36:39], v[142:145], v[162:165], v[36:39]
	v_mfma_f32_16x16x32_bf16 v[32:35], v[142:145], v[166:169], v[32:35]
	v_add_u32_e32 v142, 0x2400, v150
	v_add_u32_e32 v143, 0x4000, v150
	v_add_u32_e32 v144, 0x4400, v150
	v_mfma_f32_16x16x32_bf16 v[28:31], v[170:173], v[134:137], v[28:31]
	v_add_u32_e32 v145, 0x6000, v150
	s_nop 0
	ds_write2_b32 v141, v44, v40 offset1:16
	ds_write2_b32 v141, v45, v41 offset0:128 offset1:144
	v_mfma_f32_16x16x32_bf16 v[24:27], v[170:173], v[158:161], v[24:27]
	ds_write2_b32 v142, v46, v42 offset1:16
	ds_write2_b32 v142, v47, v43 offset0:128 offset1:144
	ds_write2_b32 v141, v36, v32 offset0:32 offset1:48
	ds_write2_b32 v141, v37, v33 offset0:160 offset1:176
	ds_write2_b32 v142, v38, v34 offset0:32 offset1:48
	ds_write2_b32 v142, v39, v35 offset0:160 offset1:176
	v_mfma_f32_16x16x32_bf16 v[20:23], v[170:173], v[162:165], v[20:23]
	s_nop 0
	ds_write2_b32 v143, v28, v24 offset1:16
	ds_write2_b32 v143, v29, v25 offset0:128 offset1:144
	v_mfma_f32_16x16x32_bf16 v[16:19], v[170:173], v[166:169], v[16:19]
	ds_write2_b32 v144, v30, v26 offset1:16
	ds_write2_b32 v144, v31, v27 offset0:128 offset1:144
	s_nop 5
	ds_write2_b32 v143, v20, v16 offset0:32 offset1:48
	ds_write2_b32 v143, v21, v17 offset0:160 offset1:176
	ds_write2_b32 v144, v22, v18 offset0:32 offset1:48
	ds_write2_b32 v144, v23, v19 offset0:160 offset1:176
	v_mfma_f32_16x16x32_bf16 v[12:15], v[174:177], v[134:137], v[12:15]
	v_mfma_f32_16x16x32_bf16 v[8:11], v[174:177], v[158:161], v[8:11]
	s_nop 7
	ds_write2_b32 v145, v12, v8 offset1:16
	ds_write2_b32 v145, v13, v9 offset0:128 offset1:144
	v_mfma_f32_16x16x32_bf16 v[4:7], v[174:177], v[162:165], v[4:7]
	ds_write2_b32 v157, v14, v10 offset1:16
	ds_write2_b32 v157, v15, v11 offset0:128 offset1:144
	v_mfma_f32_16x16x32_bf16 v[0:3], v[174:177], v[166:169], v[0:3]
	s_nop 7
	ds_write2_b32 v145, v4, v0 offset0:32 offset1:48
	ds_write2_b32 v145, v5, v1 offset0:160 offset1:176
	ds_write2_b32 v157, v6, v2 offset0:32 offset1:48
	ds_write2_b32 v157, v7, v3 offset0:160 offset1:176
	v_lshl_or_b32 v4, s48, 7, v151
	v_ashrrev_i32_e32 v5, 31, v4
	v_lshl_add_u64 v[0:1], v[4:5], 1, s[50:51]
	v_lshl_add_u64 v[2:3], v[4:5], 2, s[42:43]
	v_lshlrev_b64 v[4:5], 1, v[4:5]
	s_waitcnt lgkmcnt(0)
	s_barrier

; template <int GATE>
; DEVI void gemm_core_t(f32x4 (&acc)[4][4], const bfu* __restrict__ A, int lda,
;                     const bfu* __restrict__ B, int ldb, int K, char* smem, int tid, const bfu* __restrict__ B2 = nullptr) {
;     ...
;   for (int t = 0; t < nt; ++t) {
;     asm volatile("s_waitcnt vmcnt(0)" ::: "memory");
;     __syncthreads();
;     char* cur = smem + (t & 1) * 32768;
;     if (t + 1 < nt) {
;       char* nx = smem + ((t + 1) & 1) * 32768;
;       stage_tile(A, lda, (t + 1) * 64, nx, tid);
;       if (GATE) stage_tile_gate(B, B2, (t + 1) * 64, nx + 16384, tid); else stage_tile(B, ldb, (t + 1) * 64, nx + 16384, tid);
;     }
; #pragma unroll
;     for (int kk = 0; kk < 2; ++kk) {
;       bf16x8 af[4], bfr[4];
; #pragma unroll
;       for (int m = 0; m < 4; ++m) af[m] = ldfrag(cur, wr * 64 + m * 16 + fr, kk * 4 + fq);
; #pragma unroll
;       for (int n = 0; n < 4; ++n) bfr[n] = ldfrag(cur + 16384, wc * 64 + n * 16 + fr, kk * 4 + fq);
; #pragma unroll
;       for (int m = 0; m < 4; ++m)
; #pragma unroll
;         for (int n = 0; n < 4; ++n)
;           acc[m][n] = __builtin_amdgcn_mfma_f32_16x16x32_bf16(af[m], bfr[n], acc[m][n], 0, 0, 0);
;     }
.LBB0_739:
	s_add_i32 s27, s24, 0xffff8000
	s_and_b32 s50, s27, 0x8000
	s_and_b32 s27, s24, 0x8000
	v_add_u32_e32 v88, s27, v101
	v_or_b32_e32 v153, s50, v146
	v_readfirstlane_b32 s51, v88
	v_add_u32_e32 v88, v153, v148
	v_add_u32_e32 v153, v153, v147
	s_waitcnt vmcnt(0)
	s_waitcnt vmcnt(0) lgkmcnt(0)
	s_barrier
	ds_read_b128 v[158:161], v153
	ds_read_b128 v[174:177], v88 offset:16384
	ds_read_b128 v[178:181], v88 offset:18432
	ds_read_b128 v[196:199], v88 offset:20480
	ds_read_b128 v[200:203], v88 offset:22528
	ds_read_b128 v[162:165], v153 offset:2048
	ds_read_b128 v[166:169], v153 offset:4096
	ds_read_b128 v[170:173], v153 offset:6144
	v_lshl_add_u64 v[224:225], v[124:125], 0, s[48:49]
	s_mov_b32 m0, s51
	s_add_i32 s51, s51, 0x1000
	global_load_lds_dwordx4 v[224:225], off
	v_or_b32_e32 v88, s50, v149
	v_add_u32_e32 v153, v88, v147
	v_add_u32_e32 v88, v88, v148
	ds_read_b128 v[208:211], v88 offset:16384
	ds_read_b128 v[212:215], v88 offset:18432
	ds_read_b128 v[216:219], v88 offset:20480
	ds_read_b128 v[220:223], v88 offset:22528
	v_lshl_add_u64 v[224:225], v[126:127], 0, s[48:49]
	s_mov_b32 m0, s51
	s_add_i32 s51, s51, 0x1000
	global_load_lds_dwordx4 v[224:225], off
	s_waitcnt lgkmcnt(7)
	v_mfma_f32_16x16x32_bf16 v[60:63], v[158:161], v[174:177], v[60:63]
	v_mfma_f32_16x16x32_bf16 v[56:59], v[158:161], v[178:181], v[56:59]
	v_mfma_f32_16x16x32_bf16 v[52:55], v[158:161], v[196:199], v[52:55]
	v_mfma_f32_16x16x32_bf16 v[48:51], v[158:161], v[200:203], v[48:51]
	ds_read_b128 v[158:161], v153
	v_lshl_add_u64 v[224:225], v[128:129], 0, s[48:49]
	s_mov_b32 m0, s51
	s_add_i32 s51, s51, 0x1000
	global_load_lds_dwordx4 v[224:225], off
	s_waitcnt lgkmcnt(7)
	v_mfma_f32_16x16x32_bf16 v[44:47], v[162:165], v[174:177], v[44:47]
	v_mfma_f32_16x16x32_bf16 v[40:43], v[162:165], v[178:181], v[40:43]
	v_mfma_f32_16x16x32_bf16 v[36:39], v[162:165], v[196:199], v[36:39]
	v_mfma_f32_16x16x32_bf16 v[32:35], v[162:165], v[200:203], v[32:35]
	ds_read_b128 v[162:165], v153 offset:2048
	v_lshl_add_u64 v[224:225], v[130:131], 0, s[48:49]
	s_mov_b32 m0, s51
	s_add_i32 s51, s51, 0x1000
	global_load_lds_dwordx4 v[224:225], off
	s_waitcnt lgkmcnt(7)
	v_mfma_f32_16x16x32_bf16 v[28:31], v[166:169], v[174:177], v[28:31]
	v_mfma_f32_16x16x32_bf16 v[24:27], v[166:169], v[178:181], v[24:27]
	v_mfma_f32_16x16x32_bf16 v[20:23], v[166:169], v[196:199], v[20:23]
	v_mfma_f32_16x16x32_bf16 v[16:19], v[166:169], v[200:203], v[16:19]
	ds_read_b128 v[166:169], v153 offset:4096
	v_lshl_add_u64 v[224:225], v[132:133], 0, s[48:49]
	s_mov_b32 m0, s51
	s_add_i32 s51, s51, 0x1000
	global_load_lds_dwordx4 v[224:225], off
	s_waitcnt lgkmcnt(7)
	v_mfma_f32_16x16x32_bf16 v[12:15], v[170:173], v[174:177], v[12:15]
	v_mfma_f32_16x16x32_bf16 v[8:11], v[170:173], v[178:181], v[8:11]
	v_mfma_f32_16x16x32_bf16 v[4:7], v[170:173], v[196:199], v[4:7]
	v_mfma_f32_16x16x32_bf16 v[0:3], v[170:173], v[200:203], v[0:3]
	ds_read_b128 v[170:173], v153 offset:6144
	v_lshl_add_u64 v[224:225], v[134:135], 0, s[48:49]
	s_mov_b32 m0, s51
	s_add_i32 s51, s51, 0x1000
	global_load_lds_dwordx4 v[224:225], off
	s_waitcnt lgkmcnt(3)
	v_mfma_f32_16x16x32_bf16 v[60:63], v[158:161], v[208:211], v[60:63]
	v_mfma_f32_16x16x32_bf16 v[56:59], v[158:161], v[212:215], v[56:59]
	v_mfma_f32_16x16x32_bf16 v[52:55], v[158:161], v[216:219], v[52:55]
	v_mfma_f32_16x16x32_bf16 v[48:51], v[158:161], v[220:223], v[48:51]
	v_lshl_add_u64 v[224:225], v[136:137], 0, s[48:49]
	s_mov_b32 m0, s51
	s_add_i32 s51, s51, 0x1000
	global_load_lds_dwordx4 v[224:225], off
	s_waitcnt lgkmcnt(2)
	v_mfma_f32_16x16x32_bf16 v[44:47], v[162:165], v[208:211], v[44:47]
	v_mfma_f32_16x16x32_bf16 v[40:43], v[162:165], v[212:215], v[40:43]
	v_mfma_f32_16x16x32_bf16 v[36:39], v[162:165], v[216:219], v[36:39]
	v_mfma_f32_16x16x32_bf16 v[32:35], v[162:165], v[220:223], v[32:35]
	v_lshl_add_u64 v[224:225], v[138:139], 0, s[48:49]
	s_mov_b32 m0, s51
	s_add_i32 s51, s51, 0x1000
	global_load_lds_dwordx4 v[224:225], off
	s_waitcnt lgkmcnt(1)
	v_mfma_f32_16x16x32_bf16 v[28:31], v[166:169], v[208:211], v[28:31]
	v_mfma_f32_16x16x32_bf16 v[24:27], v[166:169], v[212:215], v[24:27]
	v_mfma_f32_16x16x32_bf16 v[20:23], v[166:169], v[216:219], v[20:23]
	v_mfma_f32_16x16x32_bf16 v[16:19], v[166:169], v[220:223], v[16:19]
	s_waitcnt lgkmcnt(0)
	v_mfma_f32_16x16x32_bf16 v[12:15], v[170:173], v[208:211], v[12:15]
	v_mfma_f32_16x16x32_bf16 v[8:11], v[170:173], v[212:215], v[8:11]
	v_mfma_f32_16x16x32_bf16 v[4:7], v[170:173], v[216:219], v[4:7]
	v_mfma_f32_16x16x32_bf16 v[0:3], v[170:173], v[220:223], v[0:3]
	s_add_u32 s48, s48, 0x80
	s_addc_u32 s49, s49, 0
	s_add_i32 s24, s24, 0x8000
	s_cmpk_lg_i32 s48, 0x780
	s_cbranch_scc1 .LBB0_739
	v_add_u32_e32 v88, s27, v146
	v_add_u32_e32 v153, v88, v147
	s_waitcnt vmcnt(0)
	s_waitcnt vmcnt(0)
	s_barrier
; template <int GATE>
; DEVI void gemm_core_t(f32x4 (&acc)[4][4], const bfu* __restrict__ A, int lda,
;                     const bfu* __restrict__ B, int ldb, int K, char* smem, int tid, const bfu* __restrict__ B2 = nullptr) {
;     ...
; #pragma unroll
;     for (int kk = 0; kk < 2; ++kk) {
;       bf16x8 af[4], bfr[4];
; #pragma unroll
;       for (int m = 0; m < 4; ++m) af[m] = ldfrag(cur, wr * 64 + m * 16 + fr, kk * 4 + fq);
; #pragma unroll
;       for (int n = 0; n < 4; ++n) bfr[n] = ldfrag(cur + 16384, wc * 64 + n * 16 + fr, kk * 4 + fq);
; #pragma unroll
;       for (int m = 0; m < 4; ++m)
; #pragma unroll
;         for (int n = 0; n < 4; ++n)
;           acc[m][n] = __builtin_amdgcn_mfma_f32_16x16x32_bf16(af[m], bfr[n], acc[m][n], 0, 0, 0);
;     }
; DEVI void epi_stage_f32(const f32x4 (&acc)[4][4], char* smem, int tid) {
;   const int wid = tid >> 6, lane = tid & 63, wr = wid >> 1, wc = wid & 1, fr = lane & 15, fq = lane >> 4;
;   float* T = reinterpret_cast<float*>(smem);
;   __syncthreads();
; #pragma unroll
;   for (int m = 0; m < 4; ++m)
; #pragma unroll
;     for (int n = 0; n < 4; ++n)
; #pragma unroll
;       for (int j = 0; j < 4; ++j)
;         T[(wr * 64 + m * 16 + fq * 4 + j) * 128 + wc * 64 + n * 16 + fr] = acc[m][n][j];
;   __syncthreads();
	ds_read_b128 v[124:127], v153
	v_add_u32_e32 v88, v88, v148
	ds_read_b128 v[128:131], v88 offset:16384
	ds_read_b128 v[132:135], v153 offset:2048
	ds_read_b128 v[136:139], v88 offset:18432
	ds_read_b128 v[158:161], v88 offset:20480
	ds_read_b128 v[162:165], v88 offset:22528
	s_waitcnt lgkmcnt(3)
	v_mfma_f32_16x16x32_bf16 v[44:47], v[132:135], v[128:131], v[44:47]
	v_add_u32_e32 v88, s27, v149
	s_add_u32 s44, s30, s44
	s_addc_u32 s45, s31, s45
	v_mfma_f32_16x16x32_bf16 v[60:63], v[124:127], v[128:131], v[60:63]
	s_add_u32 s46, s30, s46
	s_addc_u32 s47, s31, s47
	s_lshl_b64 s[40:41], s[40:41], 7
	s_waitcnt lgkmcnt(2)
	v_mfma_f32_16x16x32_bf16 v[56:59], v[124:127], v[136:139], v[56:59]
	s_mov_b32 s24, 0
	s_waitcnt lgkmcnt(1)
	v_mfma_f32_16x16x32_bf16 v[52:55], v[124:127], v[158:161], v[52:55]
	s_waitcnt lgkmcnt(0)
	v_mfma_f32_16x16x32_bf16 v[48:51], v[124:127], v[162:165], v[48:51]
	v_mfma_f32_16x16x32_bf16 v[40:43], v[132:135], v[136:139], v[40:43]
	v_mfma_f32_16x16x32_bf16 v[36:39], v[132:135], v[158:161], v[36:39]
	v_mfma_f32_16x16x32_bf16 v[32:35], v[132:135], v[162:165], v[32:35]
	ds_read_b128 v[124:127], v153 offset:4096
	ds_read_b128 v[132:135], v153 offset:6144
	v_add_u32_e32 v153, v88, v147
	v_add_u32_e32 v88, v88, v148
	s_waitcnt lgkmcnt(1)
	v_mfma_f32_16x16x32_bf16 v[28:31], v[124:127], v[128:131], v[28:31]
	v_mfma_f32_16x16x32_bf16 v[24:27], v[124:127], v[136:139], v[24:27]
	v_mfma_f32_16x16x32_bf16 v[20:23], v[124:127], v[158:161], v[20:23]
	v_mfma_f32_16x16x32_bf16 v[16:19], v[124:127], v[162:165], v[16:19]
	ds_read_b128 v[124:127], v153
	s_waitcnt lgkmcnt(1)
	v_mfma_f32_16x16x32_bf16 v[12:15], v[132:135], v[128:131], v[12:15]
	v_mfma_f32_16x16x32_bf16 v[8:11], v[132:135], v[136:139], v[8:11]
	v_mfma_f32_16x16x32_bf16 v[4:7], v[132:135], v[158:161], v[4:7]
	v_mfma_f32_16x16x32_bf16 v[0:3], v[132:135], v[162:165], v[0:3]
	ds_read_b128 v[128:131], v88 offset:16384
	ds_read_b128 v[132:135], v153 offset:2048
	ds_read_b128 v[136:139], v88 offset:18432
	ds_read_b128 v[158:161], v88 offset:20480
	ds_read_b128 v[162:165], v88 offset:22528
	s_waitcnt lgkmcnt(4)
	v_mfma_f32_16x16x32_bf16 v[60:63], v[124:127], v[128:131], v[60:63]
	s_waitcnt lgkmcnt(2)
	v_mfma_f32_16x16x32_bf16 v[56:59], v[124:127], v[136:139], v[56:59]
	s_waitcnt lgkmcnt(1)
	v_mfma_f32_16x16x32_bf16 v[52:55], v[124:127], v[158:161], v[52:55]
	s_waitcnt lgkmcnt(0)
	v_mfma_f32_16x16x32_bf16 v[48:51], v[124:127], v[162:165], v[48:51]
	ds_read_b128 v[124:127], v153 offset:4096
	ds_read_b128 v[166:169], v153 offset:6144
	s_waitcnt lgkmcnt(0)
	s_barrier
	v_mfma_f32_16x16x32_bf16 v[44:47], v[132:135], v[128:131], v[44:47]
	ds_write2_b32 v150, v60, v56 offset1:16
	ds_write2_b32 v150, v61, v57 offset0:128 offset1:144
	ds_write2_b32 v140, v62, v58 offset1:16
	ds_write2_b32 v140, v63, v59 offset0:128 offset1:144
	v_mfma_f32_16x16x32_bf16 v[40:43], v[132:135], v[136:139], v[40:43]
	ds_write2_b32 v150, v52, v48 offset0:32 offset1:48
	ds_write2_b32 v150, v53, v49 offset0:160 offset1:176
	ds_write2_b32 v140, v54, v50 offset0:32 offset1:48
	ds_write2_b32 v140, v55, v51 offset0:160 offset1:176
	s_nop 3
	ds_write2_b32 v141, v44, v40 offset1:16
	ds_write2_b32 v141, v45, v41 offset0:128 offset1:144
	v_mfma_f32_16x16x32_bf16 v[36:39], v[132:135], v[158:161], v[36:39]
	v_mfma_f32_16x16x32_bf16 v[32:35], v[132:135], v[162:165], v[32:35]
	ds_write2_b32 v142, v46, v42 offset1:16
	ds_write2_b32 v142, v47, v43 offset0:128 offset1:144
	s_nop 5
	ds_write2_b32 v141, v36, v32 offset0:32 offset1:48
	ds_write2_b32 v141, v37, v33 offset0:160 offset1:176
	ds_write2_b32 v142, v38, v34 offset0:32 offset1:48
	ds_write2_b32 v142, v39, v35 offset0:160 offset1:176
	v_mfma_f32_16x16x32_bf16 v[28:31], v[124:127], v[128:131], v[28:31]
	v_mfma_f32_16x16x32_bf16 v[24:27], v[124:127], v[136:139], v[24:27]
	s_nop 7
	ds_write2_b32 v143, v28, v24 offset1:16
	ds_write2_b32 v143, v29, v25 offset0:128 offset1:144
	ds_write2_b32 v144, v30, v26 offset1:16
	v_mfma_f32_16x16x32_bf16 v[20:23], v[124:127], v[158:161], v[20:23]
	v_mfma_f32_16x16x32_bf16 v[16:19], v[124:127], v[162:165], v[16:19]
	ds_write2_b32 v144, v31, v27 offset0:128 offset1:144
	s_nop 6
	ds_write2_b32 v143, v20, v16 offset0:32 offset1:48
	ds_write2_b32 v143, v21, v17 offset0:160 offset1:176
	v_mfma_f32_16x16x32_bf16 v[12:15], v[166:169], v[128:131], v[12:15]
	v_mfma_f32_16x16x32_bf16 v[8:11], v[166:169], v[136:139], v[8:11]
	ds_write2_b32 v144, v22, v18 offset0:32 offset1:48
	ds_write2_b32 v144, v23, v19 offset0:160 offset1:176
	s_nop 5
	ds_write2_b32 v145, v12, v8 offset1:16
	ds_write2_b32 v145, v13, v9 offset0:128 offset1:144
	ds_write2_b32 v157, v14, v10 offset1:16
	ds_write2_b32 v157, v15, v11 offset0:128 offset1:144
	v_mfma_f32_16x16x32_bf16 v[4:7], v[166:169], v[158:161], v[4:7]
	v_mfma_f32_16x16x32_bf16 v[0:3], v[166:169], v[162:165], v[0:3]
	s_nop 7
	ds_write2_b32 v145, v4, v0 offset0:32 offset1:48
	ds_write2_b32 v145, v5, v1 offset0:160 offset1:176
	ds_write2_b32 v157, v6, v2 offset0:32 offset1:48
	ds_write2_b32 v157, v7, v3 offset0:160 offset1:176
	v_lshl_or_b32 v4, s26, 7, v151
	v_ashrrev_i32_e32 v5, 31, v4
	v_lshl_add_u64 v[0:1], v[4:5], 2, s[42:43]
	v_lshl_add_u64 v[2:3], v[4:5], 1, s[46:47]
	v_lshlrev_b64 v[4:5], 1, v[4:5]
	s_waitcnt lgkmcnt(0)
	s_barrier

; template <int GATE>
; DEVI void gemm_core_t(f32x4 (&acc)[4][4], const bfu* __restrict__ A, int lda,
;                     const bfu* __restrict__ B, int ldb, int K, char* smem, int tid, const bfu* __restrict__ B2 = nullptr) {
;     ...
;   for (int t = 0; t < nt; ++t) {
;     asm volatile("s_waitcnt vmcnt(0)" ::: "memory");
;     __syncthreads();
;     char* cur = smem + (t & 1) * 32768;
;     if (t + 1 < nt) {
;       char* nx = smem + ((t + 1) & 1) * 32768;
;       stage_tile(A, lda, (t + 1) * 64, nx, tid);
;       if (GATE) stage_tile_gate(B, B2, (t + 1) * 64, nx + 16384, tid); else stage_tile(B, ldb, (t + 1) * 64, nx + 16384, tid);
;     }
; #pragma unroll
;     for (int kk = 0; kk < 2; ++kk) {
;       bf16x8 af[4], bfr[4];
; #pragma unroll
;       for (int m = 0; m < 4; ++m) af[m] = ldfrag(cur, wr * 64 + m * 16 + fr, kk * 4 + fq);
; #pragma unroll
;       for (int n = 0; n < 4; ++n) bfr[n] = ldfrag(cur + 16384, wc * 64 + n * 16 + fr, kk * 4 + fq);
; #pragma unroll
;       for (int m = 0; m < 4; ++m)
; #pragma unroll
;         for (int n = 0; n < 4; ++n)
;           acc[m][n] = __builtin_amdgcn_mfma_f32_16x16x32_bf16(af[m], bfr[n], acc[m][n], 0, 0, 0);
;     }
.LBB0_788:
	s_add_i32 s43, s41, 0xffff8000
	s_and_b32 s50, s43, 0x8000
	s_and_b32 s43, s41, 0x8000
	v_add_u32_e32 v121, s43, v146
	v_or_b32_e32 v125, s50, v150
	v_readfirstlane_b32 s51, v121
	v_add_u32_e32 v121, v125, v152
	v_add_u32_e32 v125, v125, v151
	s_waitcnt vmcnt(0)
	s_waitcnt vmcnt(0) lgkmcnt(0)
	s_barrier
	ds_read_b128 v[158:161], v125
	ds_read_b128 v[174:177], v121 offset:16384
	ds_read_b128 v[178:181], v121 offset:18432
	ds_read_b128 v[196:199], v121 offset:20480
	ds_read_b128 v[200:203], v121 offset:22528
	ds_read_b128 v[162:165], v125 offset:2048
	ds_read_b128 v[166:169], v125 offset:4096
	ds_read_b128 v[170:173], v125 offset:6144
	v_lshl_add_u64 v[224:225], v[130:131], 0, s[44:45]
	s_mov_b32 m0, s51
	s_add_i32 s51, s51, 0x1000
	global_load_lds_dwordx4 v[224:225], off
	v_or_b32_e32 v121, s50, v153
	v_add_u32_e32 v125, v121, v151
	v_add_u32_e32 v121, v121, v152
	ds_read_b128 v[208:211], v121 offset:16384
	ds_read_b128 v[212:215], v121 offset:18432
	ds_read_b128 v[216:219], v121 offset:20480
	ds_read_b128 v[220:223], v121 offset:22528
	v_lshl_add_u64 v[224:225], v[132:133], 0, s[44:45]
	s_mov_b32 m0, s51
	s_add_i32 s51, s51, 0x1000
	global_load_lds_dwordx4 v[224:225], off
	s_waitcnt lgkmcnt(7)
	v_mfma_f32_16x16x32_bf16 v[60:63], v[158:161], v[174:177], v[60:63]
	v_mfma_f32_16x16x32_bf16 v[56:59], v[158:161], v[178:181], v[56:59]
	v_mfma_f32_16x16x32_bf16 v[52:55], v[158:161], v[196:199], v[52:55]
	v_mfma_f32_16x16x32_bf16 v[48:51], v[158:161], v[200:203], v[48:51]
	ds_read_b128 v[158:161], v125
	v_lshl_add_u64 v[224:225], v[134:135], 0, s[44:45]
	s_mov_b32 m0, s51
	s_add_i32 s51, s51, 0x1000
	global_load_lds_dwordx4 v[224:225], off
	s_waitcnt lgkmcnt(7)
	v_mfma_f32_16x16x32_bf16 v[44:47], v[162:165], v[174:177], v[44:47]
	v_mfma_f32_16x16x32_bf16 v[40:43], v[162:165], v[178:181], v[40:43]
	v_mfma_f32_16x16x32_bf16 v[36:39], v[162:165], v[196:199], v[36:39]
	v_mfma_f32_16x16x32_bf16 v[32:35], v[162:165], v[200:203], v[32:35]
	ds_read_b128 v[162:165], v125 offset:2048
	v_lshl_add_u64 v[224:225], v[136:137], 0, s[44:45]
	s_mov_b32 m0, s51
	s_add_i32 s51, s51, 0x1000
	global_load_lds_dwordx4 v[224:225], off
	s_waitcnt lgkmcnt(7)
	v_mfma_f32_16x16x32_bf16 v[28:31], v[166:169], v[174:177], v[28:31]
	v_mfma_f32_16x16x32_bf16 v[24:27], v[166:169], v[178:181], v[24:27]
	v_mfma_f32_16x16x32_bf16 v[20:23], v[166:169], v[196:199], v[20:23]
	v_mfma_f32_16x16x32_bf16 v[16:19], v[166:169], v[200:203], v[16:19]
	ds_read_b128 v[166:169], v125 offset:4096
	v_lshl_add_u64 v[224:225], v[138:139], 0, s[44:45]
	s_mov_b32 m0, s51
	s_add_i32 s51, s51, 0x1000
	global_load_lds_dwordx4 v[224:225], off
	s_waitcnt lgkmcnt(7)
	v_mfma_f32_16x16x32_bf16 v[12:15], v[170:173], v[174:177], v[12:15]
	v_mfma_f32_16x16x32_bf16 v[8:11], v[170:173], v[178:181], v[8:11]
	v_mfma_f32_16x16x32_bf16 v[4:7], v[170:173], v[196:199], v[4:7]
	v_mfma_f32_16x16x32_bf16 v[0:3], v[170:173], v[200:203], v[0:3]
	ds_read_b128 v[170:173], v125 offset:6144
	v_lshl_add_u64 v[224:225], v[140:141], 0, s[44:45]
	s_mov_b32 m0, s51
	s_add_i32 s51, s51, 0x1000
	global_load_lds_dwordx4 v[224:225], off
	s_waitcnt lgkmcnt(3)
	v_mfma_f32_16x16x32_bf16 v[60:63], v[158:161], v[208:211], v[60:63]
	v_mfma_f32_16x16x32_bf16 v[56:59], v[158:161], v[212:215], v[56:59]
	v_mfma_f32_16x16x32_bf16 v[52:55], v[158:161], v[216:219], v[52:55]
	v_mfma_f32_16x16x32_bf16 v[48:51], v[158:161], v[220:223], v[48:51]
	v_lshl_add_u64 v[224:225], v[142:143], 0, s[44:45]
	s_mov_b32 m0, s51
	s_add_i32 s51, s51, 0x1000
	global_load_lds_dwordx4 v[224:225], off
	s_waitcnt lgkmcnt(2)
	v_mfma_f32_16x16x32_bf16 v[44:47], v[162:165], v[208:211], v[44:47]
	v_mfma_f32_16x16x32_bf16 v[40:43], v[162:165], v[212:215], v[40:43]
	v_mfma_f32_16x16x32_bf16 v[36:39], v[162:165], v[216:219], v[36:39]
	v_mfma_f32_16x16x32_bf16 v[32:35], v[162:165], v[220:223], v[32:35]
	v_lshl_add_u64 v[224:225], v[144:145], 0, s[44:45]
	s_mov_b32 m0, s51
	s_add_i32 s51, s51, 0x1000
	global_load_lds_dwordx4 v[224:225], off
	s_waitcnt lgkmcnt(1)
	v_mfma_f32_16x16x32_bf16 v[28:31], v[166:169], v[208:211], v[28:31]
	v_mfma_f32_16x16x32_bf16 v[24:27], v[166:169], v[212:215], v[24:27]
	v_mfma_f32_16x16x32_bf16 v[20:23], v[166:169], v[216:219], v[20:23]
	v_mfma_f32_16x16x32_bf16 v[16:19], v[166:169], v[220:223], v[16:19]
	s_waitcnt lgkmcnt(0)
	v_mfma_f32_16x16x32_bf16 v[12:15], v[170:173], v[208:211], v[12:15]
	v_mfma_f32_16x16x32_bf16 v[8:11], v[170:173], v[212:215], v[8:11]
	v_mfma_f32_16x16x32_bf16 v[4:7], v[170:173], v[216:219], v[4:7]
	v_mfma_f32_16x16x32_bf16 v[0:3], v[170:173], v[220:223], v[0:3]
	s_add_u32 s44, s44, 0x80
	s_addc_u32 s45, s45, 0
	s_add_i32 s41, s41, 0x8000
	s_cmpk_lg_i32 s44, 0x780
	s_cbranch_scc1 .LBB0_788
	v_add_u32_e32 v121, s43, v150
	v_add_u32_e32 v125, v121, v151
	s_waitcnt vmcnt(0)
	s_waitcnt vmcnt(0)
	s_barrier
; template <int GATE>
; DEVI void gemm_core_t(f32x4 (&acc)[4][4], const bfu* __restrict__ A, int lda,
;                     const bfu* __restrict__ B, int ldb, int K, char* smem, int tid, const bfu* __restrict__ B2 = nullptr) {
;     ...
; #pragma unroll
;     for (int kk = 0; kk < 2; ++kk) {
;       bf16x8 af[4], bfr[4];
; #pragma unroll
;       for (int m = 0; m < 4; ++m) af[m] = ldfrag(cur, wr * 64 + m * 16 + fr, kk * 4 + fq);
; #pragma unroll
;       for (int n = 0; n < 4; ++n) bfr[n] = ldfrag(cur + 16384, wc * 64 + n * 16 + fr, kk * 4 + fq);
; #pragma unroll
;       for (int m = 0; m < 4; ++m)
; #pragma unroll
;         for (int n = 0; n < 4; ++n)
;           acc[m][n] = __builtin_amdgcn_mfma_f32_16x16x32_bf16(af[m], bfr[n], acc[m][n], 0, 0, 0);
;     }
; DEVI void epi_stage_f32(const f32x4 (&acc)[4][4], char* smem, int tid) {
;   const int wid = tid >> 6, lane = tid & 63, wr = wid >> 1, wc = wid & 1, fr = lane & 15, fq = lane >> 4;
;   float* T = reinterpret_cast<float*>(smem);
;   __syncthreads();
; #pragma unroll
;   for (int m = 0; m < 4; ++m)
; #pragma unroll
;     for (int n = 0; n < 4; ++n)
; #pragma unroll
;       for (int j = 0; j < 4; ++j)
;         T[(wr * 64 + m * 16 + fq * 4 + j) * 128 + wc * 64 + n * 16 + fr] = acc[m][n][j];
;   __syncthreads();
	ds_read_b128 v[130:133], v125
	v_add_u32_e32 v121, v121, v152
	ds_read_b128 v[134:137], v121 offset:16384
	ds_read_b128 v[138:141], v125 offset:2048
	ds_read_b128 v[142:145], v121 offset:18432
	ds_read_b128 v[158:161], v121 offset:20480
	ds_read_b128 v[162:165], v121 offset:22528
	s_waitcnt lgkmcnt(3)
	v_mfma_f32_16x16x32_bf16 v[44:47], v[138:141], v[134:137], v[44:47]
	v_add_u32_e32 v121, s43, v153
	s_lshl_b32 s50, s40, 7
	s_mov_b32 s51, 0
	v_mfma_f32_16x16x32_bf16 v[60:63], v[130:133], v[134:137], v[60:63]
	s_waitcnt lgkmcnt(2)
	v_mfma_f32_16x16x32_bf16 v[56:59], v[130:133], v[142:145], v[56:59]
	s_waitcnt lgkmcnt(1)
	v_mfma_f32_16x16x32_bf16 v[52:55], v[130:133], v[158:161], v[52:55]
	s_waitcnt lgkmcnt(0)
	v_mfma_f32_16x16x32_bf16 v[48:51], v[130:133], v[162:165], v[48:51]
	v_mfma_f32_16x16x32_bf16 v[40:43], v[138:141], v[142:145], v[40:43]
	v_mfma_f32_16x16x32_bf16 v[36:39], v[138:141], v[158:161], v[36:39]
	v_mfma_f32_16x16x32_bf16 v[32:35], v[138:141], v[162:165], v[32:35]
	ds_read_b128 v[130:133], v125 offset:4096
	ds_read_b128 v[138:141], v125 offset:6144
	v_add_u32_e32 v125, v121, v151
	v_add_u32_e32 v121, v121, v152
	s_waitcnt lgkmcnt(1)
	v_mfma_f32_16x16x32_bf16 v[28:31], v[130:133], v[134:137], v[28:31]
	v_mfma_f32_16x16x32_bf16 v[24:27], v[130:133], v[142:145], v[24:27]
	v_mfma_f32_16x16x32_bf16 v[20:23], v[130:133], v[158:161], v[20:23]
	v_mfma_f32_16x16x32_bf16 v[16:19], v[130:133], v[162:165], v[16:19]
	ds_read_b128 v[130:133], v125
	s_waitcnt lgkmcnt(1)
	v_mfma_f32_16x16x32_bf16 v[12:15], v[138:141], v[134:137], v[12:15]
	v_mfma_f32_16x16x32_bf16 v[8:11], v[138:141], v[142:145], v[8:11]
	v_mfma_f32_16x16x32_bf16 v[4:7], v[138:141], v[158:161], v[4:7]
	v_mfma_f32_16x16x32_bf16 v[0:3], v[138:141], v[162:165], v[0:3]
	ds_read_b128 v[134:137], v121 offset:16384
	ds_read_b128 v[138:141], v125 offset:2048
	ds_read_b128 v[142:145], v121 offset:18432
	ds_read_b128 v[158:161], v121 offset:20480
	ds_read_b128 v[162:165], v121 offset:22528
	ds_read_b128 v[166:169], v125 offset:4096
	ds_read_b128 v[170:173], v125 offset:6144
	s_waitcnt lgkmcnt(6)
	v_mfma_f32_16x16x32_bf16 v[60:63], v[130:133], v[134:137], v[60:63]
	s_waitcnt lgkmcnt(0)
	s_barrier
	v_mfma_f32_16x16x32_bf16 v[56:59], v[130:133], v[142:145], v[56:59]
	s_nop 7
	ds_write2_b32 v154, v60, v56 offset1:16
	ds_write2_b32 v154, v61, v57 offset0:128 offset1:144
	v_mfma_f32_16x16x32_bf16 v[52:55], v[130:133], v[158:161], v[52:55]
	v_add_u32_e32 v56, 0x400, v154
	ds_write2_b32 v56, v62, v58 offset1:16
	ds_write2_b32 v56, v63, v59 offset0:128 offset1:144
	v_mfma_f32_16x16x32_bf16 v[48:51], v[130:133], v[162:165], v[48:51]
	s_nop 7
	ds_write2_b32 v154, v52, v48 offset0:32 offset1:48
	ds_write2_b32 v154, v53, v49 offset0:160 offset1:176
	ds_write2_b32 v56, v54, v50 offset0:32 offset1:48
	v_mfma_f32_16x16x32_bf16 v[44:47], v[138:141], v[134:137], v[44:47]
	v_add_u32_e32 v48, 0x2000, v154
	ds_write2_b32 v56, v55, v51 offset0:160 offset1:176
	v_mfma_f32_16x16x32_bf16 v[40:43], v[138:141], v[142:145], v[40:43]
	v_mfma_f32_16x16x32_bf16 v[36:39], v[138:141], v[158:161], v[36:39]
	v_mfma_f32_16x16x32_bf16 v[32:35], v[138:141], v[162:165], v[32:35]
	s_nop 5
	ds_write2_b32 v48, v44, v40 offset1:16
	v_add_u32_e32 v40, 0x2400, v154
	ds_write2_b32 v48, v45, v41 offset0:128 offset1:144
	v_mfma_f32_16x16x32_bf16 v[28:31], v[166:169], v[134:137], v[28:31]
	ds_write2_b32 v40, v46, v42 offset1:16
	ds_write2_b32 v40, v47, v43 offset0:128 offset1:144
	ds_write2_b32 v48, v36, v32 offset0:32 offset1:48
	ds_write2_b32 v48, v37, v33 offset0:160 offset1:176
	v_add_u32_e32 v32, 0x4000, v154
	v_mfma_f32_16x16x32_bf16 v[24:27], v[166:169], v[142:145], v[24:27]
	ds_write2_b32 v40, v38, v34 offset0:32 offset1:48
	ds_write2_b32 v40, v39, v35 offset0:160 offset1:176
	s_nop 5
	ds_write2_b32 v32, v28, v24 offset1:16
	ds_write2_b32 v32, v29, v25 offset0:128 offset1:144
	v_mfma_f32_16x16x32_bf16 v[20:23], v[166:169], v[158:161], v[20:23]
	v_add_u32_e32 v24, 0x4400, v154
	v_mfma_f32_16x16x32_bf16 v[16:19], v[166:169], v[162:165], v[16:19]
	ds_write2_b32 v24, v30, v26 offset1:16
	ds_write2_b32 v24, v31, v27 offset0:128 offset1:144
	s_nop 5
	ds_write2_b32 v32, v20, v16 offset0:32 offset1:48
	v_add_u32_e32 v16, 0x6000, v154
	v_mfma_f32_16x16x32_bf16 v[12:15], v[170:173], v[134:137], v[12:15]
	ds_write2_b32 v32, v21, v17 offset0:160 offset1:176
	ds_write2_b32 v24, v22, v18 offset0:32 offset1:48
	ds_write2_b32 v24, v23, v19 offset0:160 offset1:176
	v_mfma_f32_16x16x32_bf16 v[8:11], v[170:173], v[142:145], v[8:11]
	s_nop 7
	ds_write2_b32 v16, v12, v8 offset1:16
	ds_write2_b32 v16, v13, v9 offset0:128 offset1:144
	v_mfma_f32_16x16x32_bf16 v[4:7], v[170:173], v[158:161], v[4:7]
	v_add_u32_e32 v8, 0x6400, v154
	ds_write2_b32 v8, v14, v10 offset1:16
	ds_write2_b32 v8, v15, v11 offset0:128 offset1:144
	v_mfma_f32_16x16x32_bf16 v[0:3], v[170:173], v[162:165], v[0:3]
	s_nop 7
	ds_write2_b32 v16, v4, v0 offset0:32 offset1:48
	ds_write2_b32 v16, v5, v1 offset0:160 offset1:176
	ds_write2_b32 v8, v6, v2 offset0:32 offset1:48
	ds_write2_b32 v8, v7, v3 offset0:160 offset1:176
	v_lshl_or_b32 v4, s42, 7, v155
	v_ashrrev_i32_e32 v5, 31, v4
	v_lshl_add_u64 v[6:7], v[4:5], 2, s[26:27]
	s_waitcnt lgkmcnt(0)
	s_barrier
	s_branch .LBB0_791
